# E65: E64 plus the same counted lgkmcnt waits in the last P.V group of both MLA tile copies
# speedup vs baseline: 1.0041x; 1.0041x over previous
; #define PK4(P, BASE, OUT) do { u32x4 w = {cvtb(P[BASE + 0], P[BASE + 1]), cvtb(P[BASE + 2], P[BASE + 3]), \
;     cvtb(P[BASE + 4], P[BASE + 5]), cvtb(P[BASE + 6], P[BASE + 7])}; OUT = *reinterpret_cast<bf16x8*>(&w); } while (0)
; __device__ __forceinline__ void finishSM(f32x16& p0, f32x16& p1, float alpha, float& l_reg, bf16x8& pa0, bf16x8& pa1, bf16x8& pa2, bf16x8& pa3) {
; #pragma unroll
;   for (int r = 0; r < 16; ++r) p1[r] = __builtin_amdgcn_exp2f(p1[r]);
;   float ps = 0;
; #pragma unroll
;   for (int r = 0; r < 16; ++r) ps += p0[r];
; #pragma unroll
;   for (int r = 0; r < 16; ++r) ps += p1[r];
;   { auto rr = __builtin_amdgcn_permlane32_swap(__float_as_uint(ps), __float_as_uint(ps), false, false);
;     ps = __uint_as_float(rr[0]) + __uint_as_float(rr[1]); }
;   l_reg = l_reg * alpha + ps;
;     ...
;   PK4(p0, 0, pa0); PK4(p0, 8, pa1); PK4(p1, 0, pa2); PK4(p1, 8, pa3);
;     ...
; }
; template <int NQK>
; __device__ __forceinline__ void qkt(f32x16& p0, f32x16& p1, const char* Ks, const bf16x8* qr, int r32, int hi) {
;   constexpr int KROW = NQK * 32 + 16;
;   p0 = f32x16{}; p1 = f32x16{};
; #pragma unroll
;   for (int d0 = 0; d0 < NQK; ++d0) { const int cb = (d0 * 16 + hi * 8) * 2;
;     bf16x8 b0 = *reinterpret_cast<const bf16x8*>(Ks + r32 * KROW + cb);
;     bf16x8 b1 = *reinterpret_cast<const bf16x8*>(Ks + (32 + r32) * KROW + cb);
;     p0 = __builtin_amdgcn_mfma_f32_32x32x16_bf16(b0, qr[d0], p0, 0, 0, 0);
;     p1 = __builtin_amdgcn_mfma_f32_32x32x16_bf16(b1, qr[d0], p1, 0, 0, 0); }
; }
.LBB0_2539:
	s_mov_b32 s14, s44
	s_mov_b32 s44, s8
	s_mul_i32 s8, s14, 0x6400
	v_add_u32_e32 v169, s8, v174
	ds_read_b128 v[64:67], v169 offset:61952
	ds_read_b128 v[68:71], v169 offset:49152
	ds_read_b128 v[180:183], v169 offset:49184
	ds_read_b128 v[222:225], v169 offset:61984
	v_exp_f32_e32 v231, v146
	v_add_f32_e32 v146, 0, v184
	s_waitcnt lgkmcnt(2)
	v_mfma_f32_32x32x16_bf16 v[80:95], v[68:71], v[140:143], 0
	v_add_f32_e32 v146, v185, v146
	v_add_f32_e32 v146, v189, v146
	v_add_f32_e32 v146, v191, v146
	v_add_f32_e32 v146, v198, v146
	v_add_f32_e32 v146, v200, v146
	v_add_f32_e32 v146, v214, v146
	v_add_f32_e32 v146, v217, v146
	v_mfma_f32_32x32x16_bf16 v[64:79], v[64:67], v[140:143], 0
	v_add_f32_e32 v146, v215, v146
	v_add_f32_e32 v146, v218, v146
	v_add_f32_e32 v146, v199, v146
	v_add_f32_e32 v146, v201, v146
	v_add_f32_e32 v146, v216, v146
	v_add_f32_e32 v146, v219, v146
	v_add_f32_e32 v146, v220, v146
	s_waitcnt lgkmcnt(1)
	v_mfma_f32_32x32x16_bf16 v[80:95], v[180:183], v[136:139], v[80:95]
	v_add_f32_e32 v146, v221, v146
	v_exp_f32_e32 v229, v150
	v_exp_f32_e32 v226, v155
	v_exp_f32_e32 v227, v152
	v_exp_f32_e32 v228, v153
	v_exp_f32_e32 v230, v151
	v_exp_f32_e32 v148, v148
	s_waitcnt lgkmcnt(0)
	v_mfma_f32_32x32x16_bf16 v[64:79], v[222:225], v[136:139], v[64:79]
	ds_read_b128 v[180:183], v169 offset:49216
	ds_read_b128 v[222:225], v169 offset:62016
	v_exp_f32_e32 v149, v149
	v_exp_f32_e32 v232, v147
	v_cvt_pk_bf16_f32 v155, v199, v201
	v_cvt_pk_bf16_f32 v147, v229, v230
	s_waitcnt lgkmcnt(1)
	v_mfma_f32_32x32x16_bf16 v[80:95], v[180:183], v[132:135], v[80:95]
	s_waitcnt lgkmcnt(0)
	v_mfma_f32_32x32x16_bf16 v[64:79], v[222:225], v[132:135], v[64:79]
	ds_read_b128 v[180:183], v169 offset:49248
	ds_read_b128 v[222:225], v169 offset:62048
	s_waitcnt lgkmcnt(1)
	v_mfma_f32_32x32x16_bf16 v[80:95], v[180:183], v[128:131], v[80:95]
	s_waitcnt lgkmcnt(0)
	v_mfma_f32_32x32x16_bf16 v[64:79], v[222:225], v[128:131], v[64:79]
	ds_read_b128 v[180:183], v169 offset:49280
	ds_read_b128 v[222:225], v169 offset:62080
	s_waitcnt lgkmcnt(1)
	v_mfma_f32_32x32x16_bf16 v[80:95], v[180:183], v[124:127], v[80:95]
	s_waitcnt lgkmcnt(0)
	v_mfma_f32_32x32x16_bf16 v[64:79], v[222:225], v[124:127], v[64:79]
	ds_read_b128 v[180:183], v169 offset:49312
	ds_read_b128 v[222:225], v169 offset:62112
	s_waitcnt lgkmcnt(1)
	v_mfma_f32_32x32x16_bf16 v[80:95], v[180:183], v[120:123], v[80:95]
	s_waitcnt lgkmcnt(0)
	v_mfma_f32_32x32x16_bf16 v[64:79], v[222:225], v[120:123], v[64:79]
	ds_read_b128 v[180:183], v169 offset:49344
	ds_read_b128 v[222:225], v169 offset:62144
	s_waitcnt lgkmcnt(1)
	v_mfma_f32_32x32x16_bf16 v[80:95], v[180:183], v[116:119], v[80:95]
	s_waitcnt lgkmcnt(0)
	v_mfma_f32_32x32x16_bf16 v[64:79], v[222:225], v[116:119], v[64:79]
	ds_read_b128 v[180:183], v169 offset:49376
	ds_read_b128 v[222:225], v169 offset:62176
	s_waitcnt lgkmcnt(1)
	v_mfma_f32_32x32x16_bf16 v[80:95], v[180:183], v[112:115], v[80:95]
	s_waitcnt lgkmcnt(0)
	v_mfma_f32_32x32x16_bf16 v[64:79], v[222:225], v[112:115], v[64:79]
	ds_read_b128 v[180:183], v169 offset:49408
	ds_read_b128 v[222:225], v169 offset:62208
	s_waitcnt lgkmcnt(1)
	v_mfma_f32_32x32x16_bf16 v[80:95], v[180:183], v[108:111], v[80:95]
	s_waitcnt lgkmcnt(0)
	v_mfma_f32_32x32x16_bf16 v[64:79], v[222:225], v[108:111], v[64:79]
	ds_read_b128 v[180:183], v169 offset:49440
	ds_read_b128 v[222:225], v169 offset:62240
	s_waitcnt lgkmcnt(1)
	v_mfma_f32_32x32x16_bf16 v[80:95], v[180:183], v[104:107], v[80:95]
	s_waitcnt lgkmcnt(0)
	v_mfma_f32_32x32x16_bf16 v[64:79], v[222:225], v[104:107], v[64:79]
	ds_read_b128 v[180:183], v169 offset:49472
	ds_read_b128 v[222:225], v169 offset:62272
	s_waitcnt lgkmcnt(1)
	v_mfma_f32_32x32x16_bf16 v[80:95], v[180:183], v[100:103], v[80:95]
	s_waitcnt lgkmcnt(0)
	v_mfma_f32_32x32x16_bf16 v[64:79], v[222:225], v[100:103], v[64:79]
	ds_read_b128 v[180:183], v169 offset:49504
	ds_read_b128 v[222:225], v169 offset:62304
	v_exp_f32_e32 v169, v160
	v_cvt_pk_bf16_f32 v160, v198, v200
	v_add_f32_e32 v146, v169, v146
	s_waitcnt lgkmcnt(1)
	v_mfma_f32_32x32x16_bf16 v[80:95], v[180:183], v[96:99], v[80:95]
	v_exp_f32_e32 v180, v161
	v_exp_f32_e32 v183, v158
	v_cvt_pk_bf16_f32 v158, v184, v185
	v_cvt_pk_bf16_f32 v161, v214, v217
	v_add_f32_e32 v146, v180, v146
	v_cvt_pk_bf16_f32 v150, v169, v180
	v_add_f32_e32 v146, v183, v146
	s_nop 4
	v_max_f32_e32 v169, v81, v81
	v_max_f32_e32 v180, v80, v80
	s_waitcnt lgkmcnt(0)
; #define SBAR() __builtin_amdgcn_sched_barrier(0)
; __device__ __forceinline__ void decideSM(const f32x16& p0, const f32x16& p1, float& m_reg, float& mn, float& alpha, const float C, const float thr) {
;   float pmax = p0[0];
; #pragma unroll
;   for (int r = 1; r < 16; ++r) pmax = fmaxf(pmax, p0[r]);
; #pragma unroll
;   for (int r = 0; r < 16; ++r) pmax = fmaxf(pmax, p1[r]);
;   { auto rr = __builtin_amdgcn_permlane32_swap(__float_as_uint(pmax), __float_as_uint(pmax), false, false);
;     pmax = fmaxf(__uint_as_float(rr[0]), __uint_as_float(rr[1])); }
;   if (__builtin_expect(__all(pmax - m_reg <= thr), 1)) { mn = m_reg; alpha = 1.f; }
;   else { mn = fmaxf(m_reg, pmax); alpha = __builtin_amdgcn_exp2f((m_reg - mn) * C); m_reg = mn; }
; }
; __device__ __forceinline__ void finishSM(f32x16& p0, f32x16& p1, float alpha, float& l_reg, bf16x8& pa0, bf16x8& pa1, bf16x8& pa2, bf16x8& pa3) {
; #pragma unroll
;   for (int r = 0; r < 16; ++r) p1[r] = __builtin_amdgcn_exp2f(p1[r]);
;   float ps = 0;
; #pragma unroll
;   for (int r = 0; r < 16; ++r) ps += p0[r];
; #pragma unroll
;   for (int r = 0; r < 16; ++r) ps += p1[r];
;   { auto rr = __builtin_amdgcn_permlane32_swap(__float_as_uint(ps), __float_as_uint(ps), false, false);
;     ps = __uint_as_float(rr[0]) + __uint_as_float(rr[1]); }
;   l_reg = l_reg * alpha + ps;
;     ...
;   PK4(p0, 0, pa0); PK4(p0, 8, pa1); PK4(p1, 0, pa2); PK4(p1, 8, pa3);
;     ...
; }
; template <int D0> __device__ __forceinline__ void pv_one_sm(f32x16& od, int vb, bf16x8 pa0, bf16x8 pa1, bf16x8 pa2, bf16x8 pa3, f32x16& q0, f32x16& q1, const float C, const float mnC) {
;   const s16x4 l0 = tr_read<v_rd_off(D0, 0, 0)>(vb), h0 = tr_read<v_rd_off(D0, 0, 1)>(vb), l1 = tr_read<v_rd_off(D0, 1, 0)>(vb), h1 = tr_read<v_rd_off(D0, 1, 1)>(vb);
;   const s16x4 l2 = tr_read<v_rd_off(D0, 2, 0)>(vb), h2 = tr_read<v_rd_off(D0, 2, 1)>(vb), l3 = tr_read<v_rd_off(D0, 3, 0)>(vb), h3 = tr_read<v_rd_off(D0, 3, 1)>(vb);
;   asm volatile("s_waitcnt lgkmcnt(0)" ::: "memory"); SBAR();
;     ...
;   od = __builtin_amdgcn_mfma_f32_32x32x16_bf16(pa0, PK(l0, h0), od, 0, 0, 0);
;   od = __builtin_amdgcn_mfma_f32_32x32x16_bf16(pa1, PK(l1, h1), od, 0, 0, 0);
;   od = __builtin_amdgcn_mfma_f32_32x32x16_bf16(pa2, PK(l2, h2), od, 0, 0, 0);
;   od = __builtin_amdgcn_mfma_f32_32x32x16_bf16(pa3, PK(l3, h3), od, 0, 0, 0);
	v_mfma_f32_32x32x16_bf16 v[64:79], v[222:225], v[96:99], v[64:79]
	v_max_f32_e32 v169, v180, v169
	v_max3_f32 v169, v169, v82, v83
	v_max3_f32 v169, v169, v84, v85
	v_max3_f32 v169, v169, v86, v87
	v_max3_f32 v169, v169, v88, v89
	v_max3_f32 v169, v169, v90, v91
	v_exp_f32_e32 v222, v159
	v_max3_f32 v169, v169, v92, v93
	v_exp_f32_e32 v223, v156
	v_max3_f32 v169, v169, v94, v95
	v_exp_f32_e32 v224, v157
	s_nop 0
	v_max3_f32 v169, v169, v64, v65
	v_exp_f32_e32 v225, v154
	v_max3_f32 v169, v169, v66, v67
	v_add_f32_e32 v146, v222, v146
	v_max3_f32 v169, v169, v68, v69
	v_add_f32_e32 v146, v223, v146
	v_max3_f32 v169, v169, v70, v71
	v_add_f32_e32 v146, v224, v146
	v_max3_f32 v169, v169, v72, v73
	v_add_f32_e32 v146, v225, v146
	v_max3_f32 v169, v169, v74, v75
	v_add_f32_e32 v146, v226, v146
	v_max3_f32 v169, v169, v76, v77
	v_add_f32_e32 v146, v227, v146
	v_max3_f32 v169, v169, v78, v79
	v_add_f32_e32 v146, v228, v146
	v_mov_b32_e32 v180, v169
	v_add_f32_e32 v146, v229, v146
	s_nop 0
	v_permlane32_swap_b32_e32 v169, v180
	v_add_f32_e32 v146, v230, v146
	v_max_f32_e32 v180, v180, v180
	v_max_f32_e32 v169, v169, v169
	v_add_f32_e32 v146, v148, v146
	v_max_f32_e32 v169, v169, v180
	v_add_f32_e32 v146, v149, v146
	v_sub_f32_e32 v180, v169, v178
	v_add_f32_e32 v146, v231, v146
	v_cmp_ge_f32_e32 vcc, s56, v180
	v_max_f32_e32 v180, v178, v178
	v_add_f32_e32 v181, v232, v146
	v_max_f32_e32 v180, v180, v169
	v_mov_b32_e32 v182, v181
	s_cmp_eq_u64 vcc, exec
	v_sub_f32_e32 v169, v178, v180
	v_permlane32_swap_b32_e32 v181, v182
	s_cselect_b64 s[8:9], -1, 0
	v_mul_f32_e32 v169, 0x3dd53b94, v169
	v_cvt_pk_bf16_f32 v159, v189, v191
	v_cvt_pk_bf16_f32 v154, v215, v218
	v_cvt_pk_bf16_f32 v156, v216, v219
	v_cvt_pk_bf16_f32 v157, v220, v221
	v_cvt_pk_bf16_f32 v151, v183, v222
	v_cvt_pk_bf16_f32 v152, v223, v224
	v_cvt_pk_bf16_f32 v153, v225, v226
	v_cvt_pk_bf16_f32 v146, v227, v228
	v_cvt_pk_bf16_f32 v148, v148, v149
	v_cvt_pk_bf16_f32 v149, v231, v232
	s_add_i32 s10, s13, 0xfffe8000
	s_mov_b32 s38, s30
	s_mov_b32 s39, s31
	s_add_i32 s11, s13, 0xffff0000
	buffer_load_dwordx4 v[198:201], v170, s[28:31], s10 offen
	buffer_load_dwordx4 v[214:217], v170, s[28:31], s11 offen
	buffer_load_dwordx4 v[218:221], v171, s[36:39], s12 offen
	buffer_load_dwordx4 v[222:225], v176, s[36:39], s12 offen
	buffer_load_dwordx4 v[226:229], v177, s[36:39], s12 offen
	v_exp_f32_e32 v183, v169
	s_lshl_b32 s16, s44, 14
	v_add_u32_e32 v169, s16, v168
	ds_read_b64_tr_b16 v[230:231], v169 offset:0
	ds_read_b64_tr_b16 v[232:233], v169 offset:0x800
	ds_read_b64_tr_b16 v[234:235], v169 offset:0x1000
	ds_read_b64_tr_b16 v[236:237], v169 offset:0x1800
	ds_read_b64_tr_b16 v[238:239], v169 offset:0x2000
	ds_read_b64_tr_b16 v[240:241], v169 offset:0x2800
	ds_read_b64_tr_b16 v[242:243], v169 offset:0x3000
	ds_read_b64_tr_b16 v[244:245], v169 offset:0x3800
	s_waitcnt lgkmcnt(6)
	s_nop 0
	v_mfma_f32_32x32x16_bf16 v[0:15], v[158:161], v[230:233], v[0:15]
	ds_read_b64_tr_b16 v[230:231], v169 offset:0x200
	ds_read_b64_tr_b16 v[232:233], v169 offset:0xa00
	s_waitcnt lgkmcnt(6)
	v_mfma_f32_32x32x16_bf16 v[0:15], v[154:157], v[234:237], v[0:15]
	ds_read_b64_tr_b16 v[234:235], v169 offset:0x1200
	ds_read_b64_tr_b16 v[236:237], v169 offset:0x1a00
	s_waitcnt lgkmcnt(6)
	v_mfma_f32_32x32x16_bf16 v[0:15], v[150:153], v[238:241], v[0:15]
	ds_read_b64_tr_b16 v[238:239], v169 offset:0x2200
	ds_read_b64_tr_b16 v[240:241], v169 offset:0x2a00
	s_waitcnt lgkmcnt(6)
	v_mfma_f32_32x32x16_bf16 v[0:15], v[146:149], v[242:245], v[0:15]
	ds_read_b64_tr_b16 v[242:243], v169 offset:0x3200
	ds_read_b64_tr_b16 v[244:245], v169 offset:0x3a00
	s_waitcnt lgkmcnt(6)
	v_mfma_f32_32x32x16_bf16 v[48:63], v[158:161], v[230:233], v[48:63]
	ds_read_b64_tr_b16 v[230:231], v169 offset:0x400
	ds_read_b64_tr_b16 v[232:233], v169 offset:0xc00
	s_waitcnt lgkmcnt(6)
	v_mfma_f32_32x32x16_bf16 v[48:63], v[154:157], v[234:237], v[48:63]
	ds_read_b64_tr_b16 v[234:235], v169 offset:0x1400
	ds_read_b64_tr_b16 v[236:237], v169 offset:0x1c00
	s_waitcnt lgkmcnt(6)
	v_mfma_f32_32x32x16_bf16 v[48:63], v[150:153], v[238:241], v[48:63]
	ds_read_b64_tr_b16 v[238:239], v169 offset:0x2400
	ds_read_b64_tr_b16 v[240:241], v169 offset:0x2c00
	s_waitcnt lgkmcnt(6)
	v_mfma_f32_32x32x16_bf16 v[48:63], v[146:149], v[242:245], v[48:63]
	ds_read_b64_tr_b16 v[242:243], v169 offset:0x3400
	ds_read_b64_tr_b16 v[244:245], v169 offset:0x3c00
	s_waitcnt lgkmcnt(6)
	v_mfma_f32_32x32x16_bf16 v[32:47], v[158:161], v[230:233], v[32:47]
	ds_read_b64_tr_b16 v[230:231], v169 offset:0x600
	ds_read_b64_tr_b16 v[232:233], v169 offset:0xe00
	s_waitcnt lgkmcnt(6)
	v_mfma_f32_32x32x16_bf16 v[32:47], v[154:157], v[234:237], v[32:47]
	ds_read_b64_tr_b16 v[234:235], v169 offset:0x1600
	ds_read_b64_tr_b16 v[236:237], v169 offset:0x1e00
	s_waitcnt lgkmcnt(6)
	v_mfma_f32_32x32x16_bf16 v[32:47], v[150:153], v[238:241], v[32:47]
	ds_read_b64_tr_b16 v[238:239], v169 offset:0x2600
	ds_read_b64_tr_b16 v[240:241], v169 offset:0x2e00
	s_waitcnt lgkmcnt(6)
	v_mfma_f32_32x32x16_bf16 v[32:47], v[146:149], v[242:245], v[32:47]
	ds_read_b64_tr_b16 v[242:243], v169 offset:0x3600
	ds_read_b64_tr_b16 v[244:245], v169 offset:0x3e00
	s_waitcnt lgkmcnt(6)
	v_mfma_f32_32x32x16_bf16 v[16:31], v[158:161], v[230:233], v[16:31]
	s_waitcnt vmcnt(0)
	s_lshl_b32 s15, s51, 14
	s_mul_i32 s17, s51, 0x6400
	v_cndmask_b32_e64 v183, v183, 1.0, s[8:9]
	v_cmp_gt_f32_e32 vcc, 1.0, v183
	s_waitcnt lgkmcnt(4)
	v_mfma_f32_32x32x16_bf16 v[16:31], v[154:157], v[234:237], v[16:31]
	v_add_u32_e32 v154, s15, v175
	s_waitcnt vmcnt(4)
	ds_write_b128 v154, v[198:201]
	s_waitcnt vmcnt(3)
	ds_write_b128 v154, v[214:217] offset:8192
	s_waitcnt lgkmcnt(4)
	v_mfma_f32_32x32x16_bf16 v[16:31], v[150:153], v[238:241], v[16:31]
	v_add_u32_e32 v150, s17, v173
	s_waitcnt vmcnt(2)
	ds_write_b128 v150, v[218:221] offset:49152
	s_waitcnt vmcnt(1)
	ds_write_b128 v150, v[222:225] offset:49280
	s_waitcnt vmcnt(0)
	ds_write_b128 v150, v[226:229] offset:49408
	s_waitcnt lgkmcnt(5)
	v_mfma_f32_32x32x16_bf16 v[16:31], v[146:149], v[242:245], v[16:31]
	s_cbranch_vccz .LBB0_2543
; template <int NQK>
; __device__ __forceinline__ void qkt(f32x16& p0, f32x16& p1, const char* Ks, const bf16x8* qr, int r32, int hi) {
;   constexpr int KROW = NQK * 32 + 16;
;   p0 = f32x16{}; p1 = f32x16{};
; #pragma unroll
;   for (int d0 = 0; d0 < NQK; ++d0) { const int cb = (d0 * 16 + hi * 8) * 2;
;     bf16x8 b0 = *reinterpret_cast<const bf16x8*>(Ks + r32 * KROW + cb);
;     bf16x8 b1 = *reinterpret_cast<const bf16x8*>(Ks + (32 + r32) * KROW + cb);
;     p0 = __builtin_amdgcn_mfma_f32_32x32x16_bf16(b0, qr[d0], p0, 0, 0, 0);
;     p1 = __builtin_amdgcn_mfma_f32_32x32x16_bf16(b1, qr[d0], p1, 0, 0, 0); }
; }
; template <int D0> __device__ __forceinline__ void pv_one_sm(f32x16& od, int vb, bf16x8 pa0, bf16x8 pa1, bf16x8 pa2, bf16x8 pa3, f32x16& q0, f32x16& q1, const float C, const float mnC) {
;     ...
;   if (D0 < 2) {
; #pragma unroll
;     for (int r = 8 * D0; r < 8 * D0 + 8; ++r) q0[r] = __builtin_amdgcn_exp2f(fmaf(q0[r], C, mnC));
;   } else {
; #pragma unroll
;     for (int r = 8 * (D0 - 2); r < 8 * (D0 - 2) + 8; ++r) q1[r] = fmaf(q1[r], C, mnC);
;   }
	s_and_saveexec_b64 s[10:11], s[6:7]
	ds_write_b32 v166, v183 offset:128
	s_or_b64 exec, exec, s[10:11]
	s_waitcnt lgkmcnt(0)
	v_add_u32_e32 v158, v165, v162
	ds_read_b128 v[146:149], v158 offset:224
	ds_read_b128 v[150:153], v158 offset:192
	ds_read_b128 v[154:157], v158 offset:160
	ds_read_b128 v[158:161], v158 offset:128
	s_waitcnt lgkmcnt(3)
	v_pk_mul_f32 v[12:13], v[12:13], v[146:147]
	s_waitcnt lgkmcnt(2)
	v_pk_mul_f32 v[8:9], v[8:9], v[150:151]
	s_waitcnt lgkmcnt(1)
	v_pk_mul_f32 v[4:5], v[4:5], v[154:155]
	v_pk_mul_f32 v[14:15], v[14:15], v[148:149]
	v_pk_mul_f32 v[10:11], v[10:11], v[152:153]
	v_pk_mul_f32 v[6:7], v[6:7], v[156:157]
	s_waitcnt lgkmcnt(0)
	v_pk_mul_f32 v[2:3], v[2:3], v[160:161]
	v_pk_mul_f32 v[0:1], v[0:1], v[158:159]
	v_pk_mul_f32 v[60:61], v[60:61], v[146:147]
	v_pk_mul_f32 v[56:57], v[56:57], v[150:151]
	v_pk_mul_f32 v[52:53], v[52:53], v[154:155]
	v_pk_mul_f32 v[62:63], v[62:63], v[148:149]
	v_pk_mul_f32 v[58:59], v[58:59], v[152:153]
	v_pk_mul_f32 v[54:55], v[54:55], v[156:157]
	v_pk_mul_f32 v[50:51], v[50:51], v[160:161]
	v_pk_mul_f32 v[48:49], v[48:49], v[158:159]
	v_pk_mul_f32 v[44:45], v[44:45], v[146:147]
	v_pk_mul_f32 v[40:41], v[40:41], v[150:151]
	v_pk_mul_f32 v[36:37], v[36:37], v[154:155]
	v_pk_mul_f32 v[46:47], v[46:47], v[148:149]
	v_pk_mul_f32 v[42:43], v[42:43], v[152:153]
	v_pk_mul_f32 v[38:39], v[38:39], v[156:157]
	v_pk_mul_f32 v[34:35], v[34:35], v[160:161]
	v_pk_mul_f32 v[32:33], v[32:33], v[158:159]
	v_pk_mul_f32 v[28:29], v[28:29], v[146:147]
	v_pk_mul_f32 v[24:25], v[24:25], v[150:151]
	v_pk_mul_f32 v[20:21], v[20:21], v[154:155]
	v_pk_mul_f32 v[30:31], v[30:31], v[148:149]
	v_pk_mul_f32 v[26:27], v[26:27], v[152:153]
	v_pk_mul_f32 v[22:23], v[22:23], v[156:157]
	v_pk_mul_f32 v[18:19], v[18:19], v[160:161]
	v_pk_mul_f32 v[16:17], v[16:17], v[158:159]
.LBB0_2543:
	v_cndmask_b32_e64 v178, v180, v178, s[8:9]
	v_mul_f32_e32 v154, 0xbdd53b94, v178
	v_fmamk_f32 v80, v80, 0x3dd53b94, v154
	v_exp_f32_e32 v155, v80
	v_fmamk_f32 v80, v81, 0x3dd53b94, v154
	v_exp_f32_e32 v156, v80
	v_fmamk_f32 v80, v82, 0x3dd53b94, v154
	v_exp_f32_e32 v157, v80
	v_fmamk_f32 v80, v83, 0x3dd53b94, v154
	v_exp_f32_e32 v159, v80
	v_fmamk_f32 v80, v84, 0x3dd53b94, v154
	v_exp_f32_e32 v160, v80
	v_fmamk_f32 v80, v85, 0x3dd53b94, v154
	v_exp_f32_e32 v161, v80
	v_fmamk_f32 v80, v86, 0x3dd53b94, v154
	v_exp_f32_e32 v180, v80
	v_fmamk_f32 v80, v87, 0x3dd53b94, v154
	v_exp_f32_e32 v189, v80
	v_fmamk_f32 v80, v88, 0x3dd53b94, v154
	v_exp_f32_e32 v191, v80
	v_fmamk_f32 v80, v89, 0x3dd53b94, v154
	v_exp_f32_e32 v198, v80
	v_fmamk_f32 v80, v90, 0x3dd53b94, v154
	v_exp_f32_e32 v199, v80
	v_fmamk_f32 v80, v91, 0x3dd53b94, v154
	v_exp_f32_e32 v200, v80
	v_fmamk_f32 v80, v92, 0x3dd53b94, v154
	v_exp_f32_e32 v201, v80
	v_fmamk_f32 v80, v93, 0x3dd53b94, v154
	v_exp_f32_e32 v214, v80
	v_fmamk_f32 v80, v94, 0x3dd53b94, v154
	v_exp_f32_e32 v215, v80
	v_fmamk_f32 v80, v95, 0x3dd53b94, v154
	v_fmamk_f32 v184, v66, 0x3dd53b94, v154
	v_fmamk_f32 v185, v68, 0x3dd53b94, v154
	v_exp_f32_e32 v216, v80
	v_fmamk_f32 v158, v64, 0x3dd53b94, v154
	v_fmamk_f32 v217, v70, 0x3dd53b94, v154
	v_fmamk_f32 v218, v65, 0x3dd53b94, v154
	v_fmamk_f32 v219, v67, 0x3dd53b94, v154
	v_fmamk_f32 v220, v69, 0x3dd53b94, v154
	v_fmamk_f32 v221, v71, 0x3dd53b94, v154
	v_fmamk_f32 v222, v72, 0x3dd53b94, v154
	v_fmamk_f32 v223, v73, 0x3dd53b94, v154
	v_fmamk_f32 v224, v74, 0x3dd53b94, v154
	v_fmamk_f32 v225, v75, 0x3dd53b94, v154
	v_fmamk_f32 v226, v76, 0x3dd53b94, v154
	v_fmamk_f32 v227, v77, 0x3dd53b94, v154
	v_fmamk_f32 v228, v78, 0x3dd53b94, v154
	v_fmac_f32_e32 v154, 0x3dd53b94, v79
	s_waitcnt lgkmcnt(0)
	s_barrier
	v_add_u32_e32 v229, s17, v174
	ds_read_b128 v[64:67], v229 offset:61952
	ds_read_b128 v[68:71], v229 offset:49152
	ds_read_b128 v[146:149], v229 offset:49184
	ds_read_b128 v[150:153], v229 offset:61984
	v_exp_f32_e32 v217, v217
	s_waitcnt lgkmcnt(2)
	v_mfma_f32_32x32x16_bf16 v[80:95], v[68:71], v[140:143], 0
	v_mfma_f32_32x32x16_bf16 v[64:79], v[64:67], v[140:143], 0
	s_waitcnt lgkmcnt(1)
	v_mfma_f32_32x32x16_bf16 v[80:95], v[146:149], v[136:139], v[80:95]
	s_waitcnt lgkmcnt(0)
	v_mfma_f32_32x32x16_bf16 v[64:79], v[150:153], v[136:139], v[64:79]
	ds_read_b128 v[146:149], v229 offset:49216
	ds_read_b128 v[150:153], v229 offset:62016
	s_waitcnt lgkmcnt(1)
	v_mfma_f32_32x32x16_bf16 v[80:95], v[146:149], v[132:135], v[80:95]
	s_waitcnt lgkmcnt(0)
	v_mfma_f32_32x32x16_bf16 v[64:79], v[150:153], v[132:135], v[64:79]
	ds_read_b128 v[146:149], v229 offset:49248
	ds_read_b128 v[150:153], v229 offset:62048
	s_waitcnt lgkmcnt(1)
	v_mfma_f32_32x32x16_bf16 v[80:95], v[146:149], v[128:131], v[80:95]
	s_waitcnt lgkmcnt(0)
	v_mfma_f32_32x32x16_bf16 v[64:79], v[150:153], v[128:131], v[64:79]
	ds_read_b128 v[146:149], v229 offset:49280
	ds_read_b128 v[150:153], v229 offset:62080
	s_waitcnt lgkmcnt(1)
	v_mfma_f32_32x32x16_bf16 v[80:95], v[146:149], v[124:127], v[80:95]
	s_waitcnt lgkmcnt(0)
	v_mfma_f32_32x32x16_bf16 v[64:79], v[150:153], v[124:127], v[64:79]
	ds_read_b128 v[146:149], v229 offset:49312
	ds_read_b128 v[150:153], v229 offset:62112
	s_waitcnt lgkmcnt(1)
	v_mfma_f32_32x32x16_bf16 v[80:95], v[146:149], v[120:123], v[80:95]
	s_waitcnt lgkmcnt(0)
	v_mfma_f32_32x32x16_bf16 v[64:79], v[150:153], v[120:123], v[64:79]
	ds_read_b128 v[146:149], v229 offset:49344
	ds_read_b128 v[150:153], v229 offset:62144
	s_waitcnt lgkmcnt(1)
	v_mfma_f32_32x32x16_bf16 v[80:95], v[146:149], v[116:119], v[80:95]
	s_waitcnt lgkmcnt(0)
	v_mfma_f32_32x32x16_bf16 v[64:79], v[150:153], v[116:119], v[64:79]
	ds_read_b128 v[146:149], v229 offset:49376
	ds_read_b128 v[150:153], v229 offset:62176
	s_waitcnt lgkmcnt(1)
; #define SBAR() __builtin_amdgcn_sched_barrier(0)
; __device__ __forceinline__ void decideSM(const f32x16& p0, const f32x16& p1, float& m_reg, float& mn, float& alpha, const float C, const float thr) {
;   float pmax = p0[0];
; #pragma unroll
;   for (int r = 1; r < 16; ++r) pmax = fmaxf(pmax, p0[r]);
; #pragma unroll
;   for (int r = 0; r < 16; ++r) pmax = fmaxf(pmax, p1[r]);
;   { auto rr = __builtin_amdgcn_permlane32_swap(__float_as_uint(pmax), __float_as_uint(pmax), false, false);
;     pmax = fmaxf(__uint_as_float(rr[0]), __uint_as_float(rr[1])); }
;   if (__builtin_expect(__all(pmax - m_reg <= thr), 1)) { mn = m_reg; alpha = 1.f; }
;   else { mn = fmaxf(m_reg, pmax); alpha = __builtin_amdgcn_exp2f((m_reg - mn) * C); m_reg = mn; }
; }
; __device__ __forceinline__ void finishSM(f32x16& p0, f32x16& p1, float alpha, float& l_reg, bf16x8& pa0, bf16x8& pa1, bf16x8& pa2, bf16x8& pa3) {
; #pragma unroll
;   for (int r = 0; r < 16; ++r) p1[r] = __builtin_amdgcn_exp2f(p1[r]);
;   float ps = 0;
; #pragma unroll
;   for (int r = 0; r < 16; ++r) ps += p0[r];
; #pragma unroll
;   for (int r = 0; r < 16; ++r) ps += p1[r];
;   { auto rr = __builtin_amdgcn_permlane32_swap(__float_as_uint(ps), __float_as_uint(ps), false, false);
;     ps = __uint_as_float(rr[0]) + __uint_as_float(rr[1]); }
;   l_reg = l_reg * alpha + ps;
;     ...
;   PK4(p0, 0, pa0); PK4(p0, 8, pa1); PK4(p1, 0, pa2); PK4(p1, 8, pa3);
;     ...
; }
; template <int D0> __device__ __forceinline__ void pv_one_sm(f32x16& od, int vb, bf16x8 pa0, bf16x8 pa1, bf16x8 pa2, bf16x8 pa3, f32x16& q0, f32x16& q1, const float C, const float mnC) {
;   const s16x4 l0 = tr_read<v_rd_off(D0, 0, 0)>(vb), h0 = tr_read<v_rd_off(D0, 0, 1)>(vb), l1 = tr_read<v_rd_off(D0, 1, 0)>(vb), h1 = tr_read<v_rd_off(D0, 1, 1)>(vb);
;   const s16x4 l2 = tr_read<v_rd_off(D0, 2, 0)>(vb), h2 = tr_read<v_rd_off(D0, 2, 1)>(vb), l3 = tr_read<v_rd_off(D0, 3, 0)>(vb), h3 = tr_read<v_rd_off(D0, 3, 1)>(vb);
;   asm volatile("s_waitcnt lgkmcnt(0)" ::: "memory"); SBAR();
;     ...
;   od = __builtin_amdgcn_mfma_f32_32x32x16_bf16(pa0, PK(l0, h0), od, 0, 0, 0);
;   od = __builtin_amdgcn_mfma_f32_32x32x16_bf16(pa1, PK(l1, h1), od, 0, 0, 0);
;   od = __builtin_amdgcn_mfma_f32_32x32x16_bf16(pa2, PK(l2, h2), od, 0, 0, 0);
;   od = __builtin_amdgcn_mfma_f32_32x32x16_bf16(pa3, PK(l3, h3), od, 0, 0, 0);
	v_mfma_f32_32x32x16_bf16 v[80:95], v[146:149], v[112:115], v[80:95]
	s_waitcnt lgkmcnt(0)
	v_mfma_f32_32x32x16_bf16 v[64:79], v[150:153], v[112:115], v[64:79]
	ds_read_b128 v[146:149], v229 offset:49408
	ds_read_b128 v[150:153], v229 offset:62208
	s_waitcnt lgkmcnt(1)
	v_mfma_f32_32x32x16_bf16 v[80:95], v[146:149], v[108:111], v[80:95]
	s_waitcnt lgkmcnt(0)
	v_mfma_f32_32x32x16_bf16 v[64:79], v[150:153], v[108:111], v[64:79]
	ds_read_b128 v[146:149], v229 offset:49440
	ds_read_b128 v[150:153], v229 offset:62240
	s_waitcnt lgkmcnt(1)
	v_mfma_f32_32x32x16_bf16 v[80:95], v[146:149], v[104:107], v[80:95]
	s_waitcnt lgkmcnt(0)
	v_mfma_f32_32x32x16_bf16 v[64:79], v[150:153], v[104:107], v[64:79]
	ds_read_b128 v[146:149], v229 offset:49472
	ds_read_b128 v[150:153], v229 offset:62272
	s_waitcnt lgkmcnt(1)
	v_mfma_f32_32x32x16_bf16 v[80:95], v[146:149], v[100:103], v[80:95]
	s_waitcnt lgkmcnt(0)
	v_mfma_f32_32x32x16_bf16 v[64:79], v[150:153], v[100:103], v[64:79]
	ds_read_b128 v[146:149], v229 offset:49504
	ds_read_b128 v[150:153], v229 offset:62304
	s_waitcnt lgkmcnt(1)
	v_mfma_f32_32x32x16_bf16 v[80:95], v[146:149], v[96:99], v[80:95]
	v_exp_f32_e32 v146, v158
	v_exp_f32_e32 v147, v218
	v_exp_f32_e32 v148, v184
	v_exp_f32_e32 v149, v219
	v_exp_f32_e32 v218, v221
	v_exp_f32_e32 v219, v222
	v_exp_f32_e32 v221, v224
	s_waitcnt lgkmcnt(0)
	v_mfma_f32_32x32x16_bf16 v[64:79], v[150:153], v[96:99], v[64:79]
	v_add_f32_e32 v150, 0, v155
	v_add_f32_e32 v150, v156, v150
	v_add_f32_e32 v150, v157, v150
	v_add_f32_e32 v150, v159, v150
	v_add_f32_e32 v150, v160, v150
	v_add_f32_e32 v150, v161, v150
	v_add_f32_e32 v150, v180, v150
	v_add_f32_e32 v150, v189, v150
	v_add_f32_e32 v150, v191, v150
	v_cvt_pk_bf16_f32 v160, v160, v161
	v_cvt_pk_bf16_f32 v161, v180, v189
	v_max_f32_e32 v180, v81, v81
	v_max_f32_e32 v189, v80, v80
	v_add_f32_e32 v150, v198, v150
	v_max_f32_e32 v180, v189, v180
	v_add_f32_e32 v150, v199, v150
	v_max3_f32 v180, v180, v82, v83
	v_add_f32_e32 v150, v200, v150
	v_max3_f32 v180, v180, v84, v85
	v_add_f32_e32 v150, v201, v150
	v_max3_f32 v180, v180, v86, v87
	v_add_f32_e32 v150, v214, v150
	v_max3_f32 v180, v180, v88, v89
	v_add_f32_e32 v150, v215, v150
	v_max3_f32 v180, v180, v90, v91
	v_add_f32_e32 v150, v216, v150
	v_max3_f32 v180, v180, v92, v93
	v_exp_f32_e32 v152, v185
	v_add_f32_e32 v150, v146, v150
	v_max3_f32 v180, v180, v94, v95
	v_exp_f32_e32 v153, v220
	v_add_f32_e32 v150, v147, v150
	v_max3_f32 v180, v180, v64, v65
	v_add_f32_e32 v150, v148, v150
	v_max3_f32 v180, v180, v66, v67
	v_add_f32_e32 v150, v149, v150
	v_max3_f32 v180, v180, v68, v69
	v_add_f32_e32 v150, v152, v150
	v_max3_f32 v180, v180, v70, v71
	v_exp_f32_e32 v220, v223
	v_add_f32_e32 v150, v153, v150
	v_max3_f32 v180, v180, v72, v73
	v_add_f32_e32 v150, v217, v150
	v_max3_f32 v180, v180, v74, v75
	v_exp_f32_e32 v222, v225
	v_add_f32_e32 v150, v218, v150
	v_max3_f32 v180, v180, v76, v77
	v_exp_f32_e32 v223, v226
	v_add_f32_e32 v150, v219, v150
	v_max3_f32 v180, v180, v78, v79
	v_exp_f32_e32 v224, v227
	v_add_f32_e32 v150, v220, v150
	v_mov_b32_e32 v189, v180
	v_exp_f32_e32 v225, v228
	v_add_f32_e32 v150, v221, v150
	v_permlane32_swap_b32_e32 v180, v189
	v_exp_f32_e32 v226, v154
	v_add_f32_e32 v150, v222, v150
	v_max_f32_e32 v189, v189, v189
	v_max_f32_e32 v180, v180, v180
	v_add_f32_e32 v150, v223, v150
	v_max_f32_e32 v180, v180, v189
	v_add_f32_e32 v150, v224, v150
	v_sub_f32_e32 v189, v180, v178
	v_add_f32_e32 v150, v225, v150
	v_cmp_ge_f32_e32 vcc, s56, v189
	v_max_f32_e32 v189, v178, v178
	v_add_f32_e32 v184, v226, v150
	v_max_f32_e32 v189, v189, v180
	v_mov_b32_e32 v185, v184
	s_cmp_eq_u64 vcc, exec
	v_sub_f32_e32 v180, v178, v189
	v_permlane32_swap_b32_e32 v184, v185
	s_cselect_b64 s[8:9], -1, 0
	v_mul_f32_e32 v180, 0x3dd53b94, v180
	v_cvt_pk_bf16_f32 v158, v155, v156
	v_cvt_pk_bf16_f32 v159, v157, v159
	v_cvt_pk_bf16_f32 v154, v191, v198
	v_cvt_pk_bf16_f32 v155, v199, v200
	v_cvt_pk_bf16_f32 v156, v201, v214
	v_cvt_pk_bf16_f32 v157, v215, v216
	v_cvt_pk_bf16_f32 v150, v146, v147
	v_cvt_pk_bf16_f32 v151, v148, v149
	v_cvt_pk_bf16_f32 v152, v152, v153
	v_cvt_pk_bf16_f32 v153, v217, v218
	v_cvt_pk_bf16_f32 v146, v219, v220
	v_cvt_pk_bf16_f32 v147, v221, v222
	v_cvt_pk_bf16_f32 v148, v223, v224
	v_cvt_pk_bf16_f32 v149, v225, v226
	s_add_i32 s10, s13, 0xffff8000
	s_add_i32 s11, s12, 0x18000
	s_mov_b32 s38, s30
	s_mov_b32 s39, s31
	buffer_load_dwordx4 v[198:201], v170, s[28:31], s10 offen
	buffer_load_dwordx4 v[214:217], v170, s[28:31], s13 offen
	buffer_load_dwordx4 v[218:221], v171, s[36:39], s11 offen
	buffer_load_dwordx4 v[222:225], v176, s[36:39], s11 offen
	buffer_load_dwordx4 v[226:229], v177, s[36:39], s11 offen
	v_exp_f32_e32 v180, v180
	v_lshl_add_u32 v191, s14, 14, v168
	ds_read_b64_tr_b16 v[230:231], v191 offset:0
	ds_read_b64_tr_b16 v[232:233], v191 offset:0x800
	ds_read_b64_tr_b16 v[234:235], v191 offset:0x1000
	ds_read_b64_tr_b16 v[236:237], v191 offset:0x1800
	ds_read_b64_tr_b16 v[238:239], v191 offset:0x2000
	ds_read_b64_tr_b16 v[240:241], v191 offset:0x2800
	ds_read_b64_tr_b16 v[242:243], v191 offset:0x3000
	ds_read_b64_tr_b16 v[244:245], v191 offset:0x3800
	s_waitcnt lgkmcnt(6)
; #define SBAR() __builtin_amdgcn_sched_barrier(0)
; template <int D0> __device__ __forceinline__ void pv_one_sm(f32x16& od, int vb, bf16x8 pa0, bf16x8 pa1, bf16x8 pa2, bf16x8 pa3, f32x16& q0, f32x16& q1, const float C, const float mnC) {
;   const s16x4 l0 = tr_read<v_rd_off(D0, 0, 0)>(vb), h0 = tr_read<v_rd_off(D0, 0, 1)>(vb), l1 = tr_read<v_rd_off(D0, 1, 0)>(vb), h1 = tr_read<v_rd_off(D0, 1, 1)>(vb);
;   const s16x4 l2 = tr_read<v_rd_off(D0, 2, 0)>(vb), h2 = tr_read<v_rd_off(D0, 2, 1)>(vb), l3 = tr_read<v_rd_off(D0, 3, 0)>(vb), h3 = tr_read<v_rd_off(D0, 3, 1)>(vb);
;   asm volatile("s_waitcnt lgkmcnt(0)" ::: "memory"); SBAR();
;     ...
;   od = __builtin_amdgcn_mfma_f32_32x32x16_bf16(pa0, PK(l0, h0), od, 0, 0, 0);
;   od = __builtin_amdgcn_mfma_f32_32x32x16_bf16(pa1, PK(l1, h1), od, 0, 0, 0);
;   od = __builtin_amdgcn_mfma_f32_32x32x16_bf16(pa2, PK(l2, h2), od, 0, 0, 0);
;   od = __builtin_amdgcn_mfma_f32_32x32x16_bf16(pa3, PK(l3, h3), od, 0, 0, 0);
	s_nop 0
	v_mfma_f32_32x32x16_bf16 v[0:15], v[158:161], v[230:233], v[0:15]
	ds_read_b64_tr_b16 v[230:231], v191 offset:0x200
	ds_read_b64_tr_b16 v[232:233], v191 offset:0xa00
	s_waitcnt lgkmcnt(6)
	v_mfma_f32_32x32x16_bf16 v[0:15], v[154:157], v[234:237], v[0:15]
	ds_read_b64_tr_b16 v[234:235], v191 offset:0x1200
	ds_read_b64_tr_b16 v[236:237], v191 offset:0x1a00
	s_waitcnt lgkmcnt(6)
	v_mfma_f32_32x32x16_bf16 v[0:15], v[150:153], v[238:241], v[0:15]
	ds_read_b64_tr_b16 v[238:239], v191 offset:0x2200
	ds_read_b64_tr_b16 v[240:241], v191 offset:0x2a00
	s_waitcnt lgkmcnt(6)
	v_mfma_f32_32x32x16_bf16 v[0:15], v[146:149], v[242:245], v[0:15]
	ds_read_b64_tr_b16 v[242:243], v191 offset:0x3200
	ds_read_b64_tr_b16 v[244:245], v191 offset:0x3a00
	s_waitcnt lgkmcnt(6)
	v_mfma_f32_32x32x16_bf16 v[48:63], v[158:161], v[230:233], v[48:63]
	ds_read_b64_tr_b16 v[230:231], v191 offset:0x400
	ds_read_b64_tr_b16 v[232:233], v191 offset:0xc00
	s_waitcnt lgkmcnt(6)
	v_mfma_f32_32x32x16_bf16 v[48:63], v[154:157], v[234:237], v[48:63]
	ds_read_b64_tr_b16 v[234:235], v191 offset:0x1400
	ds_read_b64_tr_b16 v[236:237], v191 offset:0x1c00
	s_waitcnt lgkmcnt(6)
	v_mfma_f32_32x32x16_bf16 v[48:63], v[150:153], v[238:241], v[48:63]
	ds_read_b64_tr_b16 v[238:239], v191 offset:0x2400
	ds_read_b64_tr_b16 v[240:241], v191 offset:0x2c00
	s_waitcnt lgkmcnt(6)
	v_mfma_f32_32x32x16_bf16 v[48:63], v[146:149], v[242:245], v[48:63]
	ds_read_b64_tr_b16 v[242:243], v191 offset:0x3400
	ds_read_b64_tr_b16 v[244:245], v191 offset:0x3c00
	s_waitcnt lgkmcnt(6)
	v_mfma_f32_32x32x16_bf16 v[32:47], v[158:161], v[230:233], v[32:47]
	ds_read_b64_tr_b16 v[230:231], v191 offset:0x600
	ds_read_b64_tr_b16 v[232:233], v191 offset:0xe00
	s_waitcnt lgkmcnt(6)
	v_mfma_f32_32x32x16_bf16 v[32:47], v[154:157], v[234:237], v[32:47]
	ds_read_b64_tr_b16 v[234:235], v191 offset:0x1600
	ds_read_b64_tr_b16 v[236:237], v191 offset:0x1e00
	s_waitcnt lgkmcnt(6)
	v_mfma_f32_32x32x16_bf16 v[32:47], v[150:153], v[238:241], v[32:47]
	ds_read_b64_tr_b16 v[238:239], v191 offset:0x2600
	ds_read_b64_tr_b16 v[240:241], v191 offset:0x2e00
	s_waitcnt lgkmcnt(6)
	v_mfma_f32_32x32x16_bf16 v[32:47], v[146:149], v[242:245], v[32:47]
	ds_read_b64_tr_b16 v[242:243], v191 offset:0x3600
	ds_read_b64_tr_b16 v[244:245], v191 offset:0x3e00
	s_waitcnt lgkmcnt(6)
	v_mfma_f32_32x32x16_bf16 v[16:31], v[158:161], v[230:233], v[16:31]
	s_waitcnt vmcnt(0)
	v_cndmask_b32_e64 v180, v180, 1.0, s[8:9]
	v_cmp_gt_f32_e32 vcc, 1.0, v180
	s_waitcnt lgkmcnt(4)
	v_mfma_f32_32x32x16_bf16 v[16:31], v[154:157], v[234:237], v[16:31]
	v_add_u32_e32 v154, s16, v175
	s_mul_i32 s16, s44, 0x6400
	s_waitcnt vmcnt(4)
	ds_write_b128 v154, v[198:201]
	s_waitcnt vmcnt(3)
	ds_write_b128 v154, v[214:217] offset:8192
	s_waitcnt lgkmcnt(4)
	v_mfma_f32_32x32x16_bf16 v[16:31], v[150:153], v[238:241], v[16:31]
	v_add_u32_e32 v150, s16, v173
	s_waitcnt vmcnt(2)
	ds_write_b128 v150, v[218:221] offset:49152
	s_waitcnt vmcnt(1)
	ds_write_b128 v150, v[222:225] offset:49280
	s_waitcnt vmcnt(0)
	ds_write_b128 v150, v[226:229] offset:49408
	s_waitcnt lgkmcnt(5)
	v_mfma_f32_32x32x16_bf16 v[16:31], v[146:149], v[242:245], v[16:31]
	s_cbranch_vccz .LBB0_2547
	s_and_saveexec_b64 s[10:11], s[6:7]
	ds_write_b32 v166, v180 offset:128
	s_or_b64 exec, exec, s[10:11]
	s_waitcnt lgkmcnt(0)
	v_add_u32_e32 v158, v165, v162
	ds_read_b128 v[146:149], v158 offset:224
	ds_read_b128 v[150:153], v158 offset:192
	ds_read_b128 v[154:157], v158 offset:160
	ds_read_b128 v[158:161], v158 offset:128
	s_waitcnt lgkmcnt(3)
	v_pk_mul_f32 v[12:13], v[12:13], v[146:147]
	s_waitcnt lgkmcnt(2)
	v_pk_mul_f32 v[8:9], v[8:9], v[150:151]
	s_waitcnt lgkmcnt(1)
	v_pk_mul_f32 v[4:5], v[4:5], v[154:155]
	v_pk_mul_f32 v[14:15], v[14:15], v[148:149]
	v_pk_mul_f32 v[10:11], v[10:11], v[152:153]
	v_pk_mul_f32 v[6:7], v[6:7], v[156:157]
	s_waitcnt lgkmcnt(0)
	v_pk_mul_f32 v[2:3], v[2:3], v[160:161]
	v_pk_mul_f32 v[0:1], v[0:1], v[158:159]
	v_pk_mul_f32 v[60:61], v[60:61], v[146:147]
	v_pk_mul_f32 v[56:57], v[56:57], v[150:151]
	v_pk_mul_f32 v[52:53], v[52:53], v[154:155]
	v_pk_mul_f32 v[62:63], v[62:63], v[148:149]
	v_pk_mul_f32 v[58:59], v[58:59], v[152:153]
	v_pk_mul_f32 v[54:55], v[54:55], v[156:157]
	v_pk_mul_f32 v[50:51], v[50:51], v[160:161]
	v_pk_mul_f32 v[48:49], v[48:49], v[158:159]
	v_pk_mul_f32 v[44:45], v[44:45], v[146:147]
	v_pk_mul_f32 v[40:41], v[40:41], v[150:151]
	v_pk_mul_f32 v[36:37], v[36:37], v[154:155]
	v_pk_mul_f32 v[46:47], v[46:47], v[148:149]
	v_pk_mul_f32 v[42:43], v[42:43], v[152:153]
	v_pk_mul_f32 v[38:39], v[38:39], v[156:157]
	v_pk_mul_f32 v[34:35], v[34:35], v[160:161]
	v_pk_mul_f32 v[32:33], v[32:33], v[158:159]
	v_pk_mul_f32 v[28:29], v[28:29], v[146:147]
	v_pk_mul_f32 v[24:25], v[24:25], v[150:151]
	v_pk_mul_f32 v[20:21], v[20:21], v[154:155]
	v_pk_mul_f32 v[30:31], v[30:31], v[148:149]
	v_pk_mul_f32 v[26:27], v[26:27], v[152:153]
	v_pk_mul_f32 v[22:23], v[22:23], v[156:157]
	v_pk_mul_f32 v[18:19], v[18:19], v[160:161]
	v_pk_mul_f32 v[16:17], v[16:17], v[158:159]
